# k_rope pass: 4 rows per iteration with 16 independent loads in flight (was 1 row per iteration, latency-bound)
# speedup vs baseline: 1.0184x; 1.0023x over previous
; __device__ __forceinline__ unsigned f2bf(float f) { unsigned u = __builtin_bit_cast(unsigned, f); return (u + 0x7fffu + ((u >> 16) & 1u)) >> 16; }
; __device__ __forceinline__ void kr_pass(const bf16* ZQ, const float* rope, bf16* KR, int gw, int NGW, int lane) {
;     const int i = lane & 31;
;     for (int r = gw; r < MP; r += NGW) {
;         const int pos = pg8::row_pos(r);
;         const bf16* z = ZQ + (size_t)r * 768 + 640;
;         const float x1 = bflo((unsigned)z[i]), x2 = bflo((unsigned)z[32 + i]);
;         const float c = rope[(size_t)pos * 64 + i], s = rope[(size_t)pos * 64 + 32 + i];
;         const float y = (lane < 32) ? (x1 * c - x2 * s) : (x2 * c + x1 * s);
;         KR[(size_t)r * 64 + lane] = (bf16)f2bf(y);
;     }
; }
.LBB0_454:
	v_readfirstlane_b32 s0, v183
	s_mov_b64 s[4:5], s[90:91]
	s_mov_b64 s[8:9], s[92:93]
	s_lshr_b32 s3, s0, 6
	v_mov_b32_e32 v2, v182
	s_mov_b32 s10, s96
	s_mov_b32 s0, s70
	s_lshl_b32 s11, s0, 3
	s_add_i32 s14, s11, s3
	s_cmp_gt_i32 s14, 0x101ff
	s_cbranch_scc1 .LBB0_461
	s_lshl_b32 s2, s10, 3
	s_ashr_i32 s13, s3, 31
	s_ashr_i32 s15, s11, 31
	s_add_u32 s12, s3, s11
	s_addc_u32 s13, s13, s15
	v_and_b32_e32 v6, 31, v2
	s_lshl_b64 s[16:17], s[12:13], 7
	s_waitcnt lgkmcnt(0)
	v_lshlrev_b32_e32 v4, 2, v6
	v_mov_b32_e32 v5, 0
	s_add_u32 s4, s4, s16
	v_lshl_add_u64 v[0:1], s[8:9], 0, v[4:5]
	s_mov_b64 s[0:1], 0x3200000
	v_ashrrev_i32_e32 v3, 31, v2
	s_addc_u32 s5, s5, s17
	v_lshl_add_u64 v[0:1], v[0:1], 0, s[0:1]
	v_cmp_gt_i32_e64 s[0:1], 32, v2
	v_lshl_add_u64 v[2:3], v[2:3], 1, s[4:5]
	s_mov_b64 s[4:5], 0xe1c0000
	s_ashr_i32 s3, s2, 31
	v_lshl_add_u64 v[2:3], v[2:3], 0, s[4:5]
	s_lshl_b64 s[4:5], s[2:3], 7
	s_mul_i32 s3, s13, 0x600
	s_mul_hi_u32 s11, s12, 0x600
	s_add_i32 s11, s11, s3
	s_mul_i32 s3, s12, 0x600
	s_add_u32 s8, s8, s3
	v_lshlrev_b32_e32 v4, 1, v6
	s_addc_u32 s9, s9, s11
	v_lshl_add_u64 v[4:5], s[8:9], 0, v[4:5]
	s_mov_b64 s[8:9], 0x14200540
	v_lshl_add_u64 v[4:5], v[4:5], 0, s[8:9]
	s_mul_i32 s8, s10, 0x3000
	s_mul_hi_i32 s9, s2, 0x600
	s_movk_i32 s3, 0x7fff
	s_lshl_b64 s[36:37], s[8:9], 2
	s_lshl_b64 s[38:39], s[4:5], 2
	s_mov_b32 s35, 0
.Lkr4_l0:
	s_mul_i32 s24, s2, 3
	s_add_i32 s24, s24, s14
	s_cmp_lt_i32 s24, 0x10200
	s_cbranch_scc0 .Lkr4_done_l0
	s_mov_b32 s25, s14
	s_add_i32 s26, s25, 0x7f00
	s_and_b32 s27, s26, 0xffff
	s_mul_i32 s27, s27, 0xffc1
	s_lshr_b32 s27, s27, 30
	s_mulk_i32 s27, 0x4010
	s_sub_i32 s26, s26, s27
	s_and_b32 s26, s26, 0xffff
	s_mul_hi_i32 s27, s25, 0xfe03f81
	s_lshr_b32 s32, s27, 31
	s_ashr_i32 s27, s27, 7
	s_add_i32 s27, s27, s32
	s_mulk_i32 s27, 0x810
	s_sub_i32 s27, s25, s27
	s_cmp_gt_i32 s25, 0x80ff
	s_cselect_b32 s28, s26, s27
	s_lshl_b32 s28, s28, 8
	s_add_i32 s25, s25, s2
	s_add_i32 s26, s25, 0x7f00
	s_and_b32 s27, s26, 0xffff
	s_mul_i32 s27, s27, 0xffc1
	s_lshr_b32 s27, s27, 30
	s_mulk_i32 s27, 0x4010
	s_sub_i32 s26, s26, s27
	s_and_b32 s26, s26, 0xffff
	s_mul_hi_i32 s27, s25, 0xfe03f81
	s_lshr_b32 s32, s27, 31
	s_ashr_i32 s27, s27, 7
	s_add_i32 s27, s27, s32
	s_mulk_i32 s27, 0x810
	s_sub_i32 s27, s25, s27
	s_cmp_gt_i32 s25, 0x80ff
	s_cselect_b32 s29, s26, s27
	s_lshl_b32 s29, s29, 8
	s_add_i32 s25, s25, s2
	s_add_i32 s26, s25, 0x7f00
	s_and_b32 s27, s26, 0xffff
	s_mul_i32 s27, s27, 0xffc1
	s_lshr_b32 s27, s27, 30
	s_mulk_i32 s27, 0x4010
	s_sub_i32 s26, s26, s27
	s_and_b32 s26, s26, 0xffff
	s_mul_hi_i32 s27, s25, 0xfe03f81
	s_lshr_b32 s32, s27, 31
	s_ashr_i32 s27, s27, 7
	s_add_i32 s27, s27, s32
	s_mulk_i32 s27, 0x810
	s_sub_i32 s27, s25, s27
	s_cmp_gt_i32 s25, 0x80ff
	s_cselect_b32 s30, s26, s27
	s_lshl_b32 s30, s30, 8
	s_add_i32 s25, s25, s2
	s_add_i32 s26, s25, 0x7f00
	s_and_b32 s27, s26, 0xffff
	s_mul_i32 s27, s27, 0xffc1
	s_lshr_b32 s27, s27, 30
	s_mulk_i32 s27, 0x4010
	s_sub_i32 s26, s26, s27
	s_and_b32 s26, s26, 0xffff
	s_mul_hi_i32 s27, s25, 0xfe03f81
	s_lshr_b32 s32, s27, 31
	s_ashr_i32 s27, s27, 7
	s_add_i32 s27, s27, s32
	s_mulk_i32 s27, 0x810
	s_sub_i32 s27, s25, s27
	s_cmp_gt_i32 s25, 0x80ff
	s_cselect_b32 s31, s26, s27
	s_lshl_b32 s31, s31, 8
	v_lshl_add_u64 v[16:17], v[4:5], 0, s[8:9]
	v_lshl_add_u64 v[18:19], v[16:17], 0, s[8:9]
	v_lshl_add_u64 v[20:21], v[18:19], 0, s[8:9]
	s_mov_b32 s34, s28
	v_lshl_add_u64 v[22:23], v[0:1], 0, s[34:35]
	s_mov_b32 s34, s29
	v_lshl_add_u64 v[24:25], v[0:1], 0, s[34:35]
	s_mov_b32 s34, s30
	v_lshl_add_u64 v[26:27], v[0:1], 0, s[34:35]
	s_mov_b32 s34, s31
	v_lshl_add_u64 v[28:29], v[0:1], 0, s[34:35]
	global_load_ushort v30, v[4:5], off offset:-64
	global_load_ushort v31, v[4:5], off
	global_load_dword v32, v[22:23], off
	global_load_dword v33, v[22:23], off offset:128
	global_load_ushort v34, v[16:17], off offset:-64
	global_load_ushort v35, v[16:17], off
	global_load_dword v36, v[24:25], off
	global_load_dword v37, v[24:25], off offset:128
	global_load_ushort v38, v[18:19], off offset:-64
	global_load_ushort v39, v[18:19], off
	global_load_dword v40, v[26:27], off
	global_load_dword v41, v[26:27], off offset:128
	global_load_ushort v42, v[20:21], off offset:-64
	global_load_ushort v43, v[20:21], off
	global_load_dword v44, v[28:29], off
	global_load_dword v45, v[28:29], off offset:128
	v_lshl_add_u64 v[46:47], v[2:3], 0, s[4:5]
	v_lshl_add_u64 v[48:49], v[46:47], 0, s[4:5]
	v_lshl_add_u64 v[50:51], v[48:49], 0, s[4:5]
	s_waitcnt vmcnt(12)
	v_lshlrev_b32_e32 v6, 16, v30
	v_lshlrev_b32_e32 v7, 16, v31
	v_mov_b32_e32 v8, v32
	v_mov_b32_e32 v9, v33
	v_mov_b32_e32 v13, v8
	v_mov_b32_e32 v12, v9
	v_pk_mul_f32 v[10:11], v[8:9], v[6:7]
	v_pk_mul_f32 v[6:7], v[12:13], v[6:7]
	v_sub_f32_e32 v8, v10, v11
	v_add_f32_e32 v6, v6, v7
	v_cndmask_b32_e64 v6, v6, v8, s[0:1]
	v_bfe_u32 v7, v6, 16, 1
	v_add3_u32 v6, v6, v7, s3
	global_store_short_d16_hi v[2:3], v6, off
	s_waitcnt vmcnt(8)
	v_lshlrev_b32_e32 v6, 16, v34
	v_lshlrev_b32_e32 v7, 16, v35
	v_mov_b32_e32 v8, v36
	v_mov_b32_e32 v9, v37
	v_mov_b32_e32 v13, v8
	v_mov_b32_e32 v12, v9
	v_pk_mul_f32 v[10:11], v[8:9], v[6:7]
	v_pk_mul_f32 v[6:7], v[12:13], v[6:7]
	v_sub_f32_e32 v8, v10, v11
	v_add_f32_e32 v6, v6, v7
	v_cndmask_b32_e64 v6, v6, v8, s[0:1]
	v_bfe_u32 v7, v6, 16, 1
	v_add3_u32 v6, v6, v7, s3
	global_store_short_d16_hi v[46:47], v6, off
	s_waitcnt vmcnt(4)
	v_lshlrev_b32_e32 v6, 16, v38
	v_lshlrev_b32_e32 v7, 16, v39
	v_mov_b32_e32 v8, v40
	v_mov_b32_e32 v9, v41
	v_mov_b32_e32 v13, v8
	v_mov_b32_e32 v12, v9
	v_pk_mul_f32 v[10:11], v[8:9], v[6:7]
	v_pk_mul_f32 v[6:7], v[12:13], v[6:7]
	v_sub_f32_e32 v8, v10, v11
	v_add_f32_e32 v6, v6, v7
	v_cndmask_b32_e64 v6, v6, v8, s[0:1]
	v_bfe_u32 v7, v6, 16, 1
	v_add3_u32 v6, v6, v7, s3
	global_store_short_d16_hi v[48:49], v6, off
	s_waitcnt vmcnt(0)
	v_lshlrev_b32_e32 v6, 16, v42
	v_lshlrev_b32_e32 v7, 16, v43
	v_mov_b32_e32 v8, v44
	v_mov_b32_e32 v9, v45
	v_mov_b32_e32 v13, v8
	v_mov_b32_e32 v12, v9
	v_pk_mul_f32 v[10:11], v[8:9], v[6:7]
	v_pk_mul_f32 v[6:7], v[12:13], v[6:7]
	v_sub_f32_e32 v8, v10, v11
	v_add_f32_e32 v6, v6, v7
	v_cndmask_b32_e64 v6, v6, v8, s[0:1]
	v_bfe_u32 v7, v6, 16, 1
	v_add3_u32 v6, v6, v7, s3
	global_store_short_d16_hi v[50:51], v6, off
	s_lshl_b32 s24, s2, 2
	s_add_i32 s14, s14, s24
	v_lshl_add_u64 v[4:5], v[4:5], 0, s[36:37]
	v_lshl_add_u64 v[2:3], v[2:3], 0, s[38:39]
	s_branch .Lkr4_l0
.Lkr4_done_l0:
	s_cmp_lt_i32 s14, 0x10200
	s_cbranch_scc1 .LBB0_457
	s_branch .LBB0_461

; __device__ __forceinline__ unsigned f2bf(float f) { unsigned u = __builtin_bit_cast(unsigned, f); return (u + 0x7fffu + ((u >> 16) & 1u)) >> 16; }
; __device__ __forceinline__ void kr_pass(const bf16* ZQ, const float* rope, bf16* KR, int gw, int NGW, int lane) {
;     const int i = lane & 31;
;     for (int r = gw; r < MP; r += NGW) {
;         const int pos = pg8::row_pos(r);
;         const bf16* z = ZQ + (size_t)r * 768 + 640;
;         const float x1 = bflo((unsigned)z[i]), x2 = bflo((unsigned)z[32 + i]);
;         const float c = rope[(size_t)pos * 64 + i], s = rope[(size_t)pos * 64 + 32 + i];
;         const float y = (lane < 32) ? (x1 * c - x2 * s) : (x2 * c + x1 * s);
;         KR[(size_t)r * 64 + lane] = (bf16)f2bf(y);
;     }
; }
.LBB0_1275:
	v_readfirstlane_b32 s0, v183
	s_mov_b64 s[8:9], s[92:93]
	s_mov_b64 s[4:5], s[90:91]
	s_lshr_b32 s3, s0, 6
	v_mov_b32_e32 v2, v182
	s_mov_b32 s0, s70
	s_mov_b32 s10, s96
	s_lshl_b32 s11, s0, 3
	s_add_i32 s14, s11, s3
	s_cmp_gt_i32 s14, 0x101ff
	s_cbranch_scc1 .LBB0_1282
	s_lshl_b32 s2, s10, 3
	s_ashr_i32 s13, s3, 31
	s_ashr_i32 s15, s11, 31
	s_add_u32 s12, s3, s11
	s_addc_u32 s13, s13, s15
	v_and_b32_e32 v6, 31, v2
	s_lshl_b64 s[16:17], s[12:13], 7
	s_waitcnt lgkmcnt(0)
	v_lshlrev_b32_e32 v4, 2, v6
	v_mov_b32_e32 v5, 0
	s_add_u32 s4, s4, s16
	v_lshl_add_u64 v[0:1], s[8:9], 0, v[4:5]
	s_mov_b64 s[0:1], 0x3200000
	v_ashrrev_i32_e32 v3, 31, v2
	s_addc_u32 s5, s5, s17
	v_lshl_add_u64 v[0:1], v[0:1], 0, s[0:1]
	v_cmp_gt_i32_e64 s[0:1], 32, v2
	v_lshl_add_u64 v[2:3], v[2:3], 1, s[4:5]
	s_mov_b64 s[4:5], 0xe1c0000
	s_ashr_i32 s3, s2, 31
	v_lshl_add_u64 v[2:3], v[2:3], 0, s[4:5]
	s_lshl_b64 s[4:5], s[2:3], 7
	s_mul_i32 s3, s13, 0x600
	s_mul_hi_u32 s11, s12, 0x600
	s_add_i32 s11, s11, s3
	s_mul_i32 s3, s12, 0x600
	s_add_u32 s8, s8, s3
	v_lshlrev_b32_e32 v4, 1, v6
	s_addc_u32 s9, s9, s11
	v_lshl_add_u64 v[4:5], s[8:9], 0, v[4:5]
	s_mov_b64 s[8:9], 0x14200540
	v_lshl_add_u64 v[4:5], v[4:5], 0, s[8:9]
	s_mul_i32 s8, s10, 0x3000
	s_mul_hi_i32 s9, s2, 0x600
	s_movk_i32 s3, 0x7fff
	s_lshl_b64 s[36:37], s[8:9], 2
	s_lshl_b64 s[38:39], s[4:5], 2
	s_mov_b32 s35, 0
